# attention mode 0: workgroups start the phase staggered in 4 groups (s_sleep 0/42/84/126 by bits 3,4 of the workgroup id) to de-synchronise the per-task K/V/Q load bursts
# baseline (speedup 1.0000x reference)
.LBB0_446:
	s_or_b64 exec, exec, s[0:1]
	s_add_u32 s8, s40, 0xf000000
	s_addc_u32 s9, s41, 0
	s_add_u32 s10, s40, 0x13000000
	s_waitcnt lgkmcnt(0)
	v_mov_b32_e32 v0, v180
	s_addc_u32 s11, s41, 0
	v_mov_b32_e32 v4, v182
	s_barrier
	s_bitcmp1_b32 s2, 3
	s_cbranch_scc0 .Lsg_a_0
	s_sleep 42
.Lsg_a_0:
	s_bitcmp1_b32 s2, 4
	s_cbranch_scc0 .Lsg_b_0
	s_sleep 84
.Lsg_b_0:
	s_cmpk_gt_i32 s2, 0xfff
	v_readfirstlane_b32 s5, v4
	s_cbranch_scc1 .LBB0_463
	s_and_b32 s0, s2, 0x7ff
	s_cmpk_lt_u32 s2, 0x800
	s_cselect_b32 s60, 16, 4
	s_cselect_b32 s1, 0, 3
	s_cselect_b32 s6, 0, 2
	s_cselect_b32 s4, 4, 2
	s_and_b32 s7, s1, s2
	s_lshr_b32 s0, s0, s6
	s_add_i32 s1, s60, -1
	s_and_b32 s61, s0, s1
	s_lshr_b32 s0, s0, s4
	s_and_b32 s63, s0, 15
	s_lshr_b32 s16, s0, 4
	s_lshl_b32 s0, s16, 18
	s_lshl_b32 s1, s63, 21
	s_add_i32 s1, s1, s0
	s_lshl_b32 s95, s7, 8
	s_lshl_b32 s6, s1, 1
	s_add_u32 s36, s8, s6
	s_addc_u32 s37, s9, 0
	s_add_u32 s44, s10, s6
	v_lshrrev_b32_e32 v160, 3, v4
	v_lshlrev_b32_e32 v1, 4, v4
	s_addc_u32 s45, s11, 0
	v_lshlrev_b32_e32 v0, s4, v160
	v_and_b32_e32 v161, 0x70, v1
	v_lshl_or_b32 v80, v0, 7, v161
	s_cmp_lg_u32 s7, 0
	v_mov_b32_e32 v81, 0
	s_cselect_b64 s[0:1], -1, 0
	s_cmp_eq_u32 s7, 0
	v_lshl_add_u64 v[0:1], s[36:37], 0, v[80:81]
	v_lshl_add_u64 v[2:3], s[44:45], 0, v[80:81]
	s_cbranch_scc1 .LBB0_450
	s_add_i32 s36, s95, 0xffffff80
	s_ashr_i32 s37, s36, 31
	s_lshl_b64 s[36:37], s[36:37], s4
	s_add_u32 s36, s36, s61
	s_addc_u32 s37, s37, 0
	s_lshl_b64 s[36:37], s[36:37], 7
	v_lshl_add_u64 v[6:7], v[0:1], 0, s[36:37]
	v_lshl_add_u64 v[8:9], v[2:3], 0, s[36:37]
	global_load_dwordx4 v[84:87], v[6:7], off nt
	global_load_dwordx4 v[80:83], v[8:9], off nt
	s_andn2_b64 vcc, exec, s[0:1]
	s_mov_b32 s17, 0
	s_cbranch_vccnz .LBB0_451
